# adds: per-tile accumulator zero fill no longer executed twice (first copy moved onto the never-taken no-K path) and done with 64 v_mov_b64 instead of 128 v_mov_b32
# speedup vs baseline: 1.0069x; 1.0069x over previous
.LBB0_285:
	s_andn2_b64 vcc, exec, s[16:17]
	s_cbranch_vccz .Lzgo_1
	v_mov_b32_e32 v125, 0
	v_mov_b32_e32 v124, v125
	v_mov_b32_e32 v123, v125
	v_mov_b32_e32 v122, v125
	v_mov_b32_e32 v121, v125
	v_mov_b32_e32 v120, v125
	v_mov_b32_e32 v119, v125
	v_mov_b32_e32 v118, v125
	v_mov_b32_e32 v113, v125
	v_mov_b32_e32 v112, v125
	v_mov_b32_e32 v111, v125
	v_mov_b32_e32 v110, v125
	v_mov_b32_e32 v105, v125
	v_mov_b32_e32 v104, v125
	v_mov_b32_e32 v103, v125
	v_mov_b32_e32 v102, v125
	v_mov_b32_e32 v97, v125
	v_mov_b32_e32 v96, v125
	v_mov_b32_e32 v95, v125
	v_mov_b32_e32 v94, v125
	v_mov_b32_e32 v89, v125
	v_mov_b32_e32 v88, v125
	v_mov_b32_e32 v87, v125
	v_mov_b32_e32 v86, v125
	v_mov_b32_e32 v81, v125
	v_mov_b32_e32 v80, v125
	v_mov_b32_e32 v79, v125
	v_mov_b32_e32 v78, v125
	v_mov_b32_e32 v73, v125
	v_mov_b32_e32 v72, v125
	v_mov_b32_e32 v71, v125
	v_mov_b32_e32 v70, v125
	v_mov_b32_e32 v129, v125
	v_mov_b32_e32 v128, v125
	v_mov_b32_e32 v127, v125
	v_mov_b32_e32 v126, v125
	v_mov_b32_e32 v117, v125
	v_mov_b32_e32 v116, v125
	v_mov_b32_e32 v115, v125
	v_mov_b32_e32 v114, v125
	v_mov_b32_e32 v109, v125
	v_mov_b32_e32 v108, v125
	v_mov_b32_e32 v107, v125
	v_mov_b32_e32 v106, v125
	v_mov_b32_e32 v101, v125
	v_mov_b32_e32 v100, v125
	v_mov_b32_e32 v99, v125
	v_mov_b32_e32 v98, v125
	v_mov_b32_e32 v93, v125
	v_mov_b32_e32 v92, v125
	v_mov_b32_e32 v91, v125
	v_mov_b32_e32 v90, v125
	v_mov_b32_e32 v85, v125
	v_mov_b32_e32 v84, v125
	v_mov_b32_e32 v83, v125
	v_mov_b32_e32 v82, v125
	v_mov_b32_e32 v77, v125
	v_mov_b32_e32 v76, v125
	v_mov_b32_e32 v75, v125
	v_mov_b32_e32 v74, v125
	v_mov_b32_e32 v69, v125
	v_mov_b32_e32 v68, v125
	v_mov_b32_e32 v67, v125
	v_mov_b32_e32 v66, v125
	v_mov_b32_e32 v65, v125
	v_mov_b32_e32 v64, v125
	v_mov_b32_e32 v63, v125
	v_mov_b32_e32 v62, v125
	v_mov_b32_e32 v57, v125
	v_mov_b32_e32 v56, v125
	v_mov_b32_e32 v55, v125
	v_mov_b32_e32 v54, v125
	v_mov_b32_e32 v49, v125
	v_mov_b32_e32 v48, v125
	v_mov_b32_e32 v47, v125
	v_mov_b32_e32 v46, v125
	v_mov_b32_e32 v41, v125
	v_mov_b32_e32 v40, v125
	v_mov_b32_e32 v39, v125
	v_mov_b32_e32 v38, v125
	v_mov_b32_e32 v33, v125
	v_mov_b32_e32 v32, v125
	v_mov_b32_e32 v31, v125
	v_mov_b32_e32 v30, v125
	v_mov_b32_e32 v25, v125
	v_mov_b32_e32 v24, v125
	v_mov_b32_e32 v23, v125
	v_mov_b32_e32 v22, v125
	v_mov_b32_e32 v17, v125
	v_mov_b32_e32 v16, v125
	v_mov_b32_e32 v15, v125
	v_mov_b32_e32 v14, v125
	v_mov_b32_e32 v9, v125
	v_mov_b32_e32 v8, v125
	v_mov_b32_e32 v7, v125
	v_mov_b32_e32 v6, v125
	v_mov_b32_e32 v61, v125
	v_mov_b32_e32 v60, v125
	v_mov_b32_e32 v59, v125
	v_mov_b32_e32 v58, v125
	v_mov_b32_e32 v53, v125
	v_mov_b32_e32 v52, v125
	v_mov_b32_e32 v51, v125
	v_mov_b32_e32 v50, v125
	v_mov_b32_e32 v45, v125
	v_mov_b32_e32 v44, v125
	v_mov_b32_e32 v43, v125
	v_mov_b32_e32 v42, v125
	v_mov_b32_e32 v37, v125
	v_mov_b32_e32 v36, v125
	v_mov_b32_e32 v35, v125
	v_mov_b32_e32 v34, v125
	v_mov_b32_e32 v29, v125
	v_mov_b32_e32 v28, v125
	v_mov_b32_e32 v27, v125
	v_mov_b32_e32 v26, v125
	v_mov_b32_e32 v21, v125
	v_mov_b32_e32 v20, v125
	v_mov_b32_e32 v19, v125
	v_mov_b32_e32 v18, v125
	v_mov_b32_e32 v13, v125
	v_mov_b32_e32 v12, v125
	v_mov_b32_e32 v11, v125
	v_mov_b32_e32 v10, v125
	v_mov_b32_e32 v5, v125
	v_mov_b32_e32 v4, v125
	v_mov_b32_e32 v3, v125
	v_mov_b32_e32 v2, v125
	s_branch .LBB0_288
.Lzgo_1:
	s_add_u32 s22, s22, 0x80
	s_addc_u32 s23, s23, 0
	s_add_u32 vcc_lo, s66, 0x100
	v_mov_b64_e32 v[2:3], 0
	v_mov_b64_e32 v[4:5], 0
	v_mov_b64_e32 v[6:7], 0
	v_mov_b64_e32 v[8:9], 0
	v_mov_b64_e32 v[10:11], 0
	v_mov_b64_e32 v[12:13], 0
	v_mov_b64_e32 v[14:15], 0
	v_mov_b64_e32 v[16:17], 0
	v_mov_b64_e32 v[18:19], 0
	v_mov_b64_e32 v[20:21], 0
	v_mov_b64_e32 v[22:23], 0
	v_mov_b64_e32 v[24:25], 0
	v_mov_b64_e32 v[26:27], 0
	v_mov_b64_e32 v[28:29], 0
	v_mov_b64_e32 v[30:31], 0
	v_mov_b64_e32 v[32:33], 0
	v_mov_b64_e32 v[34:35], 0
	v_mov_b64_e32 v[36:37], 0
	v_mov_b64_e32 v[38:39], 0
	v_mov_b64_e32 v[40:41], 0
	v_mov_b64_e32 v[42:43], 0
	v_mov_b64_e32 v[44:45], 0
	v_mov_b64_e32 v[46:47], 0
	v_mov_b64_e32 v[48:49], 0
	v_mov_b64_e32 v[50:51], 0
	v_mov_b64_e32 v[52:53], 0
	v_mov_b64_e32 v[54:55], 0
	v_mov_b64_e32 v[56:57], 0
	v_mov_b64_e32 v[58:59], 0
	v_mov_b64_e32 v[60:61], 0
	v_mov_b64_e32 v[62:63], 0
	v_mov_b64_e32 v[64:65], 0
	v_mov_b64_e32 v[66:67], 0
	v_mov_b64_e32 v[68:69], 0
	v_mov_b64_e32 v[70:71], 0
	v_mov_b64_e32 v[72:73], 0
	v_mov_b64_e32 v[74:75], 0
	v_mov_b64_e32 v[76:77], 0
	v_mov_b64_e32 v[78:79], 0
	v_mov_b64_e32 v[80:81], 0
	v_mov_b64_e32 v[82:83], 0
	v_mov_b64_e32 v[84:85], 0
	v_mov_b64_e32 v[86:87], 0
	v_mov_b64_e32 v[88:89], 0
	v_mov_b64_e32 v[90:91], 0
	v_mov_b64_e32 v[92:93], 0
	v_mov_b64_e32 v[94:95], 0
	v_mov_b64_e32 v[96:97], 0
	v_mov_b64_e32 v[98:99], 0
	v_mov_b64_e32 v[100:101], 0
	v_mov_b64_e32 v[102:103], 0
	v_mov_b64_e32 v[104:105], 0
	v_mov_b64_e32 v[106:107], 0
	v_mov_b64_e32 v[108:109], 0
	v_mov_b64_e32 v[110:111], 0
	v_mov_b64_e32 v[112:113], 0
	v_mov_b64_e32 v[114:115], 0
	v_mov_b64_e32 v[116:117], 0
	v_mov_b64_e32 v[118:119], 0
	v_mov_b64_e32 v[120:121], 0
	v_mov_b64_e32 v[122:123], 0
	v_mov_b64_e32 v[124:125], 0
	v_mov_b64_e32 v[126:127], 0
	v_mov_b64_e32 v[128:129], 0
	s_addc_u32 vcc_hi, s67, 0
	s_mov_b32 s66, 0

.LBB0_358:
	s_andn2_b64 vcc, exec, s[6:7]
	s_cbranch_vccz .Lzgo_2
	v_mov_b32_e32 v129, 0
	v_mov_b32_e32 v128, v129
	v_mov_b32_e32 v127, v129
	v_mov_b32_e32 v126, v129
	v_mov_b32_e32 v97, v129
	v_mov_b32_e32 v96, v129
	v_mov_b32_e32 v95, v129
	v_mov_b32_e32 v94, v129
	v_mov_b32_e32 v125, v129
	v_mov_b32_e32 v124, v129
	v_mov_b32_e32 v123, v129
	v_mov_b32_e32 v122, v129
	v_mov_b32_e32 v93, v129
	v_mov_b32_e32 v92, v129
	v_mov_b32_e32 v91, v129
	v_mov_b32_e32 v90, v129
	v_mov_b32_e32 v121, v129
	v_mov_b32_e32 v120, v129
	v_mov_b32_e32 v119, v129
	v_mov_b32_e32 v118, v129
	v_mov_b32_e32 v89, v129
	v_mov_b32_e32 v88, v129
	v_mov_b32_e32 v87, v129
	v_mov_b32_e32 v86, v129
	v_mov_b32_e32 v117, v129
	v_mov_b32_e32 v116, v129
	v_mov_b32_e32 v115, v129
	v_mov_b32_e32 v114, v129
	v_mov_b32_e32 v85, v129
	v_mov_b32_e32 v84, v129
	v_mov_b32_e32 v83, v129
	v_mov_b32_e32 v82, v129
	v_mov_b32_e32 v65, v129
	v_mov_b32_e32 v64, v129
	v_mov_b32_e32 v63, v129
	v_mov_b32_e32 v62, v129
	v_mov_b32_e32 v33, v129
	v_mov_b32_e32 v32, v129
	v_mov_b32_e32 v31, v129
	v_mov_b32_e32 v30, v129
	v_mov_b32_e32 v61, v129
	v_mov_b32_e32 v60, v129
	v_mov_b32_e32 v59, v129
	v_mov_b32_e32 v58, v129
	v_mov_b32_e32 v29, v129
	v_mov_b32_e32 v28, v129
	v_mov_b32_e32 v27, v129
	v_mov_b32_e32 v26, v129
	v_mov_b32_e32 v57, v129
	v_mov_b32_e32 v56, v129
	v_mov_b32_e32 v55, v129
	v_mov_b32_e32 v54, v129
	v_mov_b32_e32 v25, v129
	v_mov_b32_e32 v24, v129
	v_mov_b32_e32 v23, v129
	v_mov_b32_e32 v22, v129
	v_mov_b32_e32 v53, v129
	v_mov_b32_e32 v52, v129
	v_mov_b32_e32 v51, v129
	v_mov_b32_e32 v50, v129
	v_mov_b32_e32 v21, v129
	v_mov_b32_e32 v20, v129
	v_mov_b32_e32 v19, v129
	v_mov_b32_e32 v18, v129
	v_mov_b32_e32 v113, v129
	v_mov_b32_e32 v112, v129
	v_mov_b32_e32 v111, v129
	v_mov_b32_e32 v110, v129
	v_mov_b32_e32 v81, v129
	v_mov_b32_e32 v80, v129
	v_mov_b32_e32 v79, v129
	v_mov_b32_e32 v78, v129
	v_mov_b32_e32 v109, v129
	v_mov_b32_e32 v108, v129
	v_mov_b32_e32 v107, v129
	v_mov_b32_e32 v106, v129
	v_mov_b32_e32 v77, v129
	v_mov_b32_e32 v76, v129
	v_mov_b32_e32 v75, v129
	v_mov_b32_e32 v74, v129
	v_mov_b32_e32 v105, v129
	v_mov_b32_e32 v104, v129
	v_mov_b32_e32 v103, v129
	v_mov_b32_e32 v102, v129
	v_mov_b32_e32 v73, v129
	v_mov_b32_e32 v72, v129
	v_mov_b32_e32 v71, v129
	v_mov_b32_e32 v70, v129
	v_mov_b32_e32 v101, v129
	v_mov_b32_e32 v100, v129
	v_mov_b32_e32 v99, v129
	v_mov_b32_e32 v98, v129
	v_mov_b32_e32 v69, v129
	v_mov_b32_e32 v68, v129
	v_mov_b32_e32 v67, v129
	v_mov_b32_e32 v66, v129
	v_mov_b32_e32 v49, v129
	v_mov_b32_e32 v48, v129
	v_mov_b32_e32 v47, v129
	v_mov_b32_e32 v46, v129
	v_mov_b32_e32 v17, v129
	v_mov_b32_e32 v16, v129
	v_mov_b32_e32 v15, v129
	v_mov_b32_e32 v14, v129
	v_mov_b32_e32 v45, v129
	v_mov_b32_e32 v44, v129
	v_mov_b32_e32 v43, v129
	v_mov_b32_e32 v42, v129
	v_mov_b32_e32 v13, v129
	v_mov_b32_e32 v12, v129
	v_mov_b32_e32 v11, v129
	v_mov_b32_e32 v10, v129
	v_mov_b32_e32 v41, v129
	v_mov_b32_e32 v40, v129
	v_mov_b32_e32 v39, v129
	v_mov_b32_e32 v38, v129
	v_mov_b32_e32 v9, v129
	v_mov_b32_e32 v8, v129
	v_mov_b32_e32 v7, v129
	v_mov_b32_e32 v6, v129
	v_mov_b32_e32 v37, v129
	v_mov_b32_e32 v36, v129
	v_mov_b32_e32 v35, v129
	v_mov_b32_e32 v34, v129
	v_mov_b32_e32 v5, v129
	v_mov_b32_e32 v4, v129
	v_mov_b32_e32 v3, v129
	v_mov_b32_e32 v2, v129
	s_branch .LBB0_361
.Lzgo_2:
	s_add_u32 s20, s20, 0x80
	s_addc_u32 s21, s21, 0
	s_add_u32 vcc_lo, s22, 0x100
	v_mov_b64_e32 v[2:3], 0
	v_mov_b64_e32 v[4:5], 0
	v_mov_b64_e32 v[6:7], 0
	v_mov_b64_e32 v[8:9], 0
	v_mov_b64_e32 v[10:11], 0
	v_mov_b64_e32 v[12:13], 0
	v_mov_b64_e32 v[14:15], 0
	v_mov_b64_e32 v[16:17], 0
	v_mov_b64_e32 v[18:19], 0
	v_mov_b64_e32 v[20:21], 0
	v_mov_b64_e32 v[22:23], 0
	v_mov_b64_e32 v[24:25], 0
	v_mov_b64_e32 v[26:27], 0
	v_mov_b64_e32 v[28:29], 0
	v_mov_b64_e32 v[30:31], 0
	v_mov_b64_e32 v[32:33], 0
	v_mov_b64_e32 v[34:35], 0
	v_mov_b64_e32 v[36:37], 0
	v_mov_b64_e32 v[38:39], 0
	v_mov_b64_e32 v[40:41], 0
	v_mov_b64_e32 v[42:43], 0
	v_mov_b64_e32 v[44:45], 0
	v_mov_b64_e32 v[46:47], 0
	v_mov_b64_e32 v[48:49], 0
	v_mov_b64_e32 v[50:51], 0
	v_mov_b64_e32 v[52:53], 0
	v_mov_b64_e32 v[54:55], 0
	v_mov_b64_e32 v[56:57], 0
	v_mov_b64_e32 v[58:59], 0
	v_mov_b64_e32 v[60:61], 0
	v_mov_b64_e32 v[62:63], 0
	v_mov_b64_e32 v[64:65], 0
	v_mov_b64_e32 v[66:67], 0
	v_mov_b64_e32 v[68:69], 0
	v_mov_b64_e32 v[70:71], 0
	v_mov_b64_e32 v[72:73], 0
	v_mov_b64_e32 v[74:75], 0
	v_mov_b64_e32 v[76:77], 0
	v_mov_b64_e32 v[78:79], 0
	v_mov_b64_e32 v[80:81], 0
	v_mov_b64_e32 v[82:83], 0
	v_mov_b64_e32 v[84:85], 0
	v_mov_b64_e32 v[86:87], 0
	v_mov_b64_e32 v[88:89], 0
	v_mov_b64_e32 v[90:91], 0
	v_mov_b64_e32 v[92:93], 0
	v_mov_b64_e32 v[94:95], 0
	v_mov_b64_e32 v[96:97], 0
	v_mov_b64_e32 v[98:99], 0
	v_mov_b64_e32 v[100:101], 0
	v_mov_b64_e32 v[102:103], 0
	v_mov_b64_e32 v[104:105], 0
	v_mov_b64_e32 v[106:107], 0
	v_mov_b64_e32 v[108:109], 0
	v_mov_b64_e32 v[110:111], 0
	v_mov_b64_e32 v[112:113], 0
	v_mov_b64_e32 v[114:115], 0
	v_mov_b64_e32 v[116:117], 0
	v_mov_b64_e32 v[118:119], 0
	v_mov_b64_e32 v[120:121], 0
	v_mov_b64_e32 v[122:123], 0
	v_mov_b64_e32 v[124:125], 0
	v_mov_b64_e32 v[126:127], 0
	v_mov_b64_e32 v[128:129], 0
	s_addc_u32 vcc_hi, s23, 0
	s_mov_b32 s22, 0

.LBB0_490:
	s_andn2_b64 vcc, exec, s[12:13]
	s_cbranch_vccz .Lzgo_3
	v_mov_b32_e32 v125, 0
	v_mov_b32_e32 v124, v125
	v_mov_b32_e32 v123, v125
	v_mov_b32_e32 v122, v125
	v_mov_b32_e32 v129, v125
	v_mov_b32_e32 v128, v125
	v_mov_b32_e32 v127, v125
	v_mov_b32_e32 v126, v125
	v_mov_b32_e32 v121, v125
	v_mov_b32_e32 v120, v125
	v_mov_b32_e32 v119, v125
	v_mov_b32_e32 v118, v125
	v_mov_b32_e32 v117, v125
	v_mov_b32_e32 v116, v125
	v_mov_b32_e32 v115, v125
	v_mov_b32_e32 v114, v125
	v_mov_b32_e32 v113, v125
	v_mov_b32_e32 v112, v125
	v_mov_b32_e32 v111, v125
	v_mov_b32_e32 v110, v125
	v_mov_b32_e32 v109, v125
	v_mov_b32_e32 v108, v125
	v_mov_b32_e32 v107, v125
	v_mov_b32_e32 v106, v125
	v_mov_b32_e32 v105, v125
	v_mov_b32_e32 v104, v125
	v_mov_b32_e32 v103, v125
	v_mov_b32_e32 v102, v125
	v_mov_b32_e32 v101, v125
	v_mov_b32_e32 v100, v125
	v_mov_b32_e32 v99, v125
	v_mov_b32_e32 v98, v125
	v_mov_b32_e32 v65, v125
	v_mov_b32_e32 v64, v125
	v_mov_b32_e32 v63, v125
	v_mov_b32_e32 v62, v125
	v_mov_b32_e32 v61, v125
	v_mov_b32_e32 v60, v125
	v_mov_b32_e32 v59, v125
	v_mov_b32_e32 v58, v125
	v_mov_b32_e32 v57, v125
	v_mov_b32_e32 v56, v125
	v_mov_b32_e32 v55, v125
	v_mov_b32_e32 v54, v125
	v_mov_b32_e32 v53, v125
	v_mov_b32_e32 v52, v125
	v_mov_b32_e32 v51, v125
	v_mov_b32_e32 v50, v125
	v_mov_b32_e32 v49, v125
	v_mov_b32_e32 v48, v125
	v_mov_b32_e32 v47, v125
	v_mov_b32_e32 v46, v125
	v_mov_b32_e32 v45, v125
	v_mov_b32_e32 v44, v125
	v_mov_b32_e32 v43, v125
	v_mov_b32_e32 v42, v125
	v_mov_b32_e32 v41, v125
	v_mov_b32_e32 v40, v125
	v_mov_b32_e32 v39, v125
	v_mov_b32_e32 v38, v125
	v_mov_b32_e32 v37, v125
	v_mov_b32_e32 v36, v125
	v_mov_b32_e32 v35, v125
	v_mov_b32_e32 v34, v125
	v_mov_b32_e32 v97, v125
	v_mov_b32_e32 v96, v125
	v_mov_b32_e32 v95, v125
	v_mov_b32_e32 v94, v125
	v_mov_b32_e32 v93, v125
	v_mov_b32_e32 v92, v125
	v_mov_b32_e32 v91, v125
	v_mov_b32_e32 v90, v125
	v_mov_b32_e32 v89, v125
	v_mov_b32_e32 v88, v125
	v_mov_b32_e32 v87, v125
	v_mov_b32_e32 v86, v125
	v_mov_b32_e32 v85, v125
	v_mov_b32_e32 v84, v125
	v_mov_b32_e32 v83, v125
	v_mov_b32_e32 v82, v125
	v_mov_b32_e32 v81, v125
	v_mov_b32_e32 v80, v125
	v_mov_b32_e32 v79, v125
	v_mov_b32_e32 v78, v125
	v_mov_b32_e32 v77, v125
	v_mov_b32_e32 v76, v125
	v_mov_b32_e32 v75, v125
	v_mov_b32_e32 v74, v125
	v_mov_b32_e32 v73, v125
	v_mov_b32_e32 v72, v125
	v_mov_b32_e32 v71, v125
	v_mov_b32_e32 v70, v125
	v_mov_b32_e32 v69, v125
	v_mov_b32_e32 v68, v125
	v_mov_b32_e32 v67, v125
	v_mov_b32_e32 v66, v125
	v_mov_b32_e32 v33, v125
	v_mov_b32_e32 v32, v125
	v_mov_b32_e32 v31, v125
	v_mov_b32_e32 v30, v125
	v_mov_b32_e32 v29, v125
	v_mov_b32_e32 v28, v125
	v_mov_b32_e32 v27, v125
	v_mov_b32_e32 v26, v125
	v_mov_b32_e32 v25, v125
	v_mov_b32_e32 v24, v125
	v_mov_b32_e32 v23, v125
	v_mov_b32_e32 v22, v125
	v_mov_b32_e32 v21, v125
	v_mov_b32_e32 v20, v125
	v_mov_b32_e32 v19, v125
	v_mov_b32_e32 v18, v125
	v_mov_b32_e32 v17, v125
	v_mov_b32_e32 v16, v125
	v_mov_b32_e32 v15, v125
	v_mov_b32_e32 v14, v125
	v_mov_b32_e32 v13, v125
	v_mov_b32_e32 v12, v125
	v_mov_b32_e32 v11, v125
	v_mov_b32_e32 v10, v125
	v_mov_b32_e32 v9, v125
	v_mov_b32_e32 v8, v125
	v_mov_b32_e32 v7, v125
	v_mov_b32_e32 v6, v125
	v_mov_b32_e32 v5, v125
	v_mov_b32_e32 v4, v125
	v_mov_b32_e32 v3, v125
	v_mov_b32_e32 v2, v125
	s_branch .LBB0_493
.Lzgo_3:
	s_add_u32 s18, s18, 0x80
	s_addc_u32 s19, s19, 0
	s_add_u32 s71, s20, 0x100
	v_mov_b64_e32 v[2:3], 0
	v_mov_b64_e32 v[4:5], 0
	v_mov_b64_e32 v[6:7], 0
	v_mov_b64_e32 v[8:9], 0
	v_mov_b64_e32 v[10:11], 0
	v_mov_b64_e32 v[12:13], 0
	v_mov_b64_e32 v[14:15], 0
	v_mov_b64_e32 v[16:17], 0
	v_mov_b64_e32 v[18:19], 0
	v_mov_b64_e32 v[20:21], 0
	v_mov_b64_e32 v[22:23], 0
	v_mov_b64_e32 v[24:25], 0
	v_mov_b64_e32 v[26:27], 0
	v_mov_b64_e32 v[28:29], 0
	v_mov_b64_e32 v[30:31], 0
	v_mov_b64_e32 v[32:33], 0
	v_mov_b64_e32 v[34:35], 0
	v_mov_b64_e32 v[36:37], 0
	v_mov_b64_e32 v[38:39], 0
	v_mov_b64_e32 v[40:41], 0
	v_mov_b64_e32 v[42:43], 0
	v_mov_b64_e32 v[44:45], 0
	v_mov_b64_e32 v[46:47], 0
	v_mov_b64_e32 v[48:49], 0
	v_mov_b64_e32 v[50:51], 0
	v_mov_b64_e32 v[52:53], 0
	v_mov_b64_e32 v[54:55], 0
	v_mov_b64_e32 v[56:57], 0
	v_mov_b64_e32 v[58:59], 0
	v_mov_b64_e32 v[60:61], 0
	v_mov_b64_e32 v[62:63], 0
	v_mov_b64_e32 v[64:65], 0
	v_mov_b64_e32 v[66:67], 0
	v_mov_b64_e32 v[68:69], 0
	v_mov_b64_e32 v[70:71], 0
	v_mov_b64_e32 v[72:73], 0
	v_mov_b64_e32 v[74:75], 0
	v_mov_b64_e32 v[76:77], 0
	v_mov_b64_e32 v[78:79], 0
	v_mov_b64_e32 v[80:81], 0
	v_mov_b64_e32 v[82:83], 0
	v_mov_b64_e32 v[84:85], 0
	v_mov_b64_e32 v[86:87], 0
	v_mov_b64_e32 v[88:89], 0
	v_mov_b64_e32 v[90:91], 0
	v_mov_b64_e32 v[92:93], 0
	v_mov_b64_e32 v[94:95], 0
	v_mov_b64_e32 v[96:97], 0
	v_mov_b64_e32 v[98:99], 0
	v_mov_b64_e32 v[100:101], 0
	v_mov_b64_e32 v[102:103], 0
	v_mov_b64_e32 v[104:105], 0
	v_mov_b64_e32 v[106:107], 0
	v_mov_b64_e32 v[108:109], 0
	v_mov_b64_e32 v[110:111], 0
	v_mov_b64_e32 v[112:113], 0
	v_mov_b64_e32 v[114:115], 0
	v_mov_b64_e32 v[116:117], 0
	v_mov_b64_e32 v[118:119], 0
	v_mov_b64_e32 v[120:121], 0
	v_mov_b64_e32 v[122:123], 0
	v_mov_b64_e32 v[124:125], 0
	v_mov_b64_e32 v[126:127], 0
	v_mov_b64_e32 v[128:129], 0
	s_addc_u32 s72, s21, 0
	s_mov_b32 s20, 0

.LBB0_1010:
	s_andn2_b64 vcc, exec, s[12:13]
	s_cbranch_vccz .Lzgo_5
	v_mov_b32_e32 v129, 0
	v_mov_b32_e32 v128, v129
	v_mov_b32_e32 v127, v129
	v_mov_b32_e32 v126, v129
	v_mov_b32_e32 v97, v129
	v_mov_b32_e32 v96, v129
	v_mov_b32_e32 v95, v129
	v_mov_b32_e32 v94, v129
	v_mov_b32_e32 v125, v129
	v_mov_b32_e32 v124, v129
	v_mov_b32_e32 v123, v129
	v_mov_b32_e32 v122, v129
	v_mov_b32_e32 v93, v129
	v_mov_b32_e32 v92, v129
	v_mov_b32_e32 v91, v129
	v_mov_b32_e32 v90, v129
	v_mov_b32_e32 v121, v129
	v_mov_b32_e32 v120, v129
	v_mov_b32_e32 v119, v129
	v_mov_b32_e32 v118, v129
	v_mov_b32_e32 v89, v129
	v_mov_b32_e32 v88, v129
	v_mov_b32_e32 v87, v129
	v_mov_b32_e32 v86, v129
	v_mov_b32_e32 v117, v129
	v_mov_b32_e32 v116, v129
	v_mov_b32_e32 v115, v129
	v_mov_b32_e32 v114, v129
	v_mov_b32_e32 v85, v129
	v_mov_b32_e32 v84, v129
	v_mov_b32_e32 v83, v129
	v_mov_b32_e32 v82, v129
	v_mov_b32_e32 v65, v129
	v_mov_b32_e32 v64, v129
	v_mov_b32_e32 v63, v129
	v_mov_b32_e32 v62, v129
	v_mov_b32_e32 v33, v129
	v_mov_b32_e32 v32, v129
	v_mov_b32_e32 v31, v129
	v_mov_b32_e32 v30, v129
	v_mov_b32_e32 v61, v129
	v_mov_b32_e32 v60, v129
	v_mov_b32_e32 v59, v129
	v_mov_b32_e32 v58, v129
	v_mov_b32_e32 v29, v129
	v_mov_b32_e32 v28, v129
	v_mov_b32_e32 v27, v129
	v_mov_b32_e32 v26, v129
	v_mov_b32_e32 v57, v129
	v_mov_b32_e32 v56, v129
	v_mov_b32_e32 v55, v129
	v_mov_b32_e32 v54, v129
	v_mov_b32_e32 v25, v129
	v_mov_b32_e32 v24, v129
	v_mov_b32_e32 v23, v129
	v_mov_b32_e32 v22, v129
	v_mov_b32_e32 v53, v129
	v_mov_b32_e32 v52, v129
	v_mov_b32_e32 v51, v129
	v_mov_b32_e32 v50, v129
	v_mov_b32_e32 v21, v129
	v_mov_b32_e32 v20, v129
	v_mov_b32_e32 v19, v129
	v_mov_b32_e32 v18, v129
	v_mov_b32_e32 v113, v129
	v_mov_b32_e32 v112, v129
	v_mov_b32_e32 v111, v129
	v_mov_b32_e32 v110, v129
	v_mov_b32_e32 v81, v129
	v_mov_b32_e32 v80, v129
	v_mov_b32_e32 v79, v129
	v_mov_b32_e32 v78, v129
	v_mov_b32_e32 v109, v129
	v_mov_b32_e32 v108, v129
	v_mov_b32_e32 v107, v129
	v_mov_b32_e32 v106, v129
	v_mov_b32_e32 v77, v129
	v_mov_b32_e32 v76, v129
	v_mov_b32_e32 v75, v129
	v_mov_b32_e32 v74, v129
	v_mov_b32_e32 v105, v129
	v_mov_b32_e32 v104, v129
	v_mov_b32_e32 v103, v129
	v_mov_b32_e32 v102, v129
	v_mov_b32_e32 v73, v129
	v_mov_b32_e32 v72, v129
	v_mov_b32_e32 v71, v129
	v_mov_b32_e32 v70, v129
	v_mov_b32_e32 v101, v129
	v_mov_b32_e32 v100, v129
	v_mov_b32_e32 v99, v129
	v_mov_b32_e32 v98, v129
	v_mov_b32_e32 v69, v129
	v_mov_b32_e32 v68, v129
	v_mov_b32_e32 v67, v129
	v_mov_b32_e32 v66, v129
	v_mov_b32_e32 v49, v129
	v_mov_b32_e32 v48, v129
	v_mov_b32_e32 v47, v129
	v_mov_b32_e32 v46, v129
	v_mov_b32_e32 v17, v129
	v_mov_b32_e32 v16, v129
	v_mov_b32_e32 v15, v129
	v_mov_b32_e32 v14, v129
	v_mov_b32_e32 v45, v129
	v_mov_b32_e32 v44, v129
	v_mov_b32_e32 v43, v129
	v_mov_b32_e32 v42, v129
	v_mov_b32_e32 v13, v129
	v_mov_b32_e32 v12, v129
	v_mov_b32_e32 v11, v129
	v_mov_b32_e32 v10, v129
	v_mov_b32_e32 v41, v129
	v_mov_b32_e32 v40, v129
	v_mov_b32_e32 v39, v129
	v_mov_b32_e32 v38, v129
	v_mov_b32_e32 v9, v129
	v_mov_b32_e32 v8, v129
	v_mov_b32_e32 v7, v129
	v_mov_b32_e32 v6, v129
	v_mov_b32_e32 v37, v129
	v_mov_b32_e32 v36, v129
	v_mov_b32_e32 v35, v129
	v_mov_b32_e32 v34, v129
	v_mov_b32_e32 v5, v129
	v_mov_b32_e32 v4, v129
	v_mov_b32_e32 v3, v129
	v_mov_b32_e32 v2, v129
	s_branch .LBB0_1013
.Lzgo_5:
	s_add_u32 s18, s18, 0x80
	s_addc_u32 s19, s19, 0
	s_add_u32 s71, s20, 0x100
	v_mov_b64_e32 v[2:3], 0
	v_mov_b64_e32 v[4:5], 0
	v_mov_b64_e32 v[6:7], 0
	v_mov_b64_e32 v[8:9], 0
	v_mov_b64_e32 v[10:11], 0
	v_mov_b64_e32 v[12:13], 0
	v_mov_b64_e32 v[14:15], 0
	v_mov_b64_e32 v[16:17], 0
	v_mov_b64_e32 v[18:19], 0
	v_mov_b64_e32 v[20:21], 0
	v_mov_b64_e32 v[22:23], 0
	v_mov_b64_e32 v[24:25], 0
	v_mov_b64_e32 v[26:27], 0
	v_mov_b64_e32 v[28:29], 0
	v_mov_b64_e32 v[30:31], 0
	v_mov_b64_e32 v[32:33], 0
	v_mov_b64_e32 v[34:35], 0
	v_mov_b64_e32 v[36:37], 0
	v_mov_b64_e32 v[38:39], 0
	v_mov_b64_e32 v[40:41], 0
	v_mov_b64_e32 v[42:43], 0
	v_mov_b64_e32 v[44:45], 0
	v_mov_b64_e32 v[46:47], 0
	v_mov_b64_e32 v[48:49], 0
	v_mov_b64_e32 v[50:51], 0
	v_mov_b64_e32 v[52:53], 0
	v_mov_b64_e32 v[54:55], 0
	v_mov_b64_e32 v[56:57], 0
	v_mov_b64_e32 v[58:59], 0
	v_mov_b64_e32 v[60:61], 0
	v_mov_b64_e32 v[62:63], 0
	v_mov_b64_e32 v[64:65], 0
	v_mov_b64_e32 v[66:67], 0
	v_mov_b64_e32 v[68:69], 0
	v_mov_b64_e32 v[70:71], 0
	v_mov_b64_e32 v[72:73], 0
	v_mov_b64_e32 v[74:75], 0
	v_mov_b64_e32 v[76:77], 0
	v_mov_b64_e32 v[78:79], 0
	v_mov_b64_e32 v[80:81], 0
	v_mov_b64_e32 v[82:83], 0
	v_mov_b64_e32 v[84:85], 0
	v_mov_b64_e32 v[86:87], 0
	v_mov_b64_e32 v[88:89], 0
	v_mov_b64_e32 v[90:91], 0
	v_mov_b64_e32 v[92:93], 0
	v_mov_b64_e32 v[94:95], 0
	v_mov_b64_e32 v[96:97], 0
	v_mov_b64_e32 v[98:99], 0
	v_mov_b64_e32 v[100:101], 0
	v_mov_b64_e32 v[102:103], 0
	v_mov_b64_e32 v[104:105], 0
	v_mov_b64_e32 v[106:107], 0
	v_mov_b64_e32 v[108:109], 0
	v_mov_b64_e32 v[110:111], 0
	v_mov_b64_e32 v[112:113], 0
	v_mov_b64_e32 v[114:115], 0
	v_mov_b64_e32 v[116:117], 0
	v_mov_b64_e32 v[118:119], 0
	v_mov_b64_e32 v[120:121], 0
	v_mov_b64_e32 v[122:123], 0
	v_mov_b64_e32 v[124:125], 0
	v_mov_b64_e32 v[126:127], 0
	v_mov_b64_e32 v[128:129], 0
	s_addc_u32 s72, s21, 0
	s_mov_b32 s20, 0
	s_waitcnt vmcnt(0)

.LBB0_1457:
	s_andn2_b64 vcc, exec, s[12:13]
	s_waitcnt vmcnt(0)
	s_cbranch_vccz .Lzgo_6
	v_mov_b32_e32 v129, 0
	v_mov_b32_e32 v128, v129
	v_mov_b32_e32 v127, v129
	v_mov_b32_e32 v126, v129
	v_mov_b32_e32 v97, v129
	v_mov_b32_e32 v96, v129
	v_mov_b32_e32 v95, v129
	v_mov_b32_e32 v94, v129
	v_mov_b32_e32 v125, v129
	v_mov_b32_e32 v124, v129
	v_mov_b32_e32 v123, v129
	v_mov_b32_e32 v122, v129
	v_mov_b32_e32 v93, v129
	v_mov_b32_e32 v92, v129
	v_mov_b32_e32 v91, v129
	v_mov_b32_e32 v90, v129
	v_mov_b32_e32 v121, v129
	v_mov_b32_e32 v120, v129
	v_mov_b32_e32 v119, v129
	v_mov_b32_e32 v118, v129
	v_mov_b32_e32 v89, v129
	v_mov_b32_e32 v88, v129
	v_mov_b32_e32 v87, v129
	v_mov_b32_e32 v86, v129
	v_mov_b32_e32 v117, v129
	v_mov_b32_e32 v116, v129
	v_mov_b32_e32 v115, v129
	v_mov_b32_e32 v114, v129
	v_mov_b32_e32 v85, v129
	v_mov_b32_e32 v84, v129
	v_mov_b32_e32 v83, v129
	v_mov_b32_e32 v82, v129
	v_mov_b32_e32 v65, v129
	v_mov_b32_e32 v64, v129
	v_mov_b32_e32 v63, v129
	v_mov_b32_e32 v62, v129
	v_mov_b32_e32 v33, v129
	v_mov_b32_e32 v32, v129
	v_mov_b32_e32 v31, v129
	v_mov_b32_e32 v30, v129
	v_mov_b32_e32 v61, v129
	v_mov_b32_e32 v60, v129
	v_mov_b32_e32 v59, v129
	v_mov_b32_e32 v58, v129
	v_mov_b32_e32 v29, v129
	v_mov_b32_e32 v28, v129
	v_mov_b32_e32 v27, v129
	v_mov_b32_e32 v26, v129
	v_mov_b32_e32 v57, v129
	v_mov_b32_e32 v56, v129
	v_mov_b32_e32 v55, v129
	v_mov_b32_e32 v54, v129
	v_mov_b32_e32 v25, v129
	v_mov_b32_e32 v24, v129
	v_mov_b32_e32 v23, v129
	v_mov_b32_e32 v22, v129
	v_mov_b32_e32 v53, v129
	v_mov_b32_e32 v52, v129
	v_mov_b32_e32 v51, v129
	v_mov_b32_e32 v50, v129
	v_mov_b32_e32 v21, v129
	v_mov_b32_e32 v20, v129
	v_mov_b32_e32 v19, v129
	v_mov_b32_e32 v18, v129
	v_mov_b32_e32 v113, v129
	v_mov_b32_e32 v112, v129
	v_mov_b32_e32 v111, v129
	v_mov_b32_e32 v110, v129
	v_mov_b32_e32 v81, v129
	v_mov_b32_e32 v80, v129
	v_mov_b32_e32 v79, v129
	v_mov_b32_e32 v78, v129
	v_mov_b32_e32 v109, v129
	v_mov_b32_e32 v108, v129
	v_mov_b32_e32 v107, v129
	v_mov_b32_e32 v106, v129
	v_mov_b32_e32 v77, v129
	v_mov_b32_e32 v76, v129
	v_mov_b32_e32 v75, v129
	v_mov_b32_e32 v74, v129
	v_mov_b32_e32 v105, v129
	v_mov_b32_e32 v104, v129
	v_mov_b32_e32 v103, v129
	v_mov_b32_e32 v102, v129
	v_mov_b32_e32 v73, v129
	v_mov_b32_e32 v72, v129
	v_mov_b32_e32 v71, v129
	v_mov_b32_e32 v70, v129
	v_mov_b32_e32 v101, v129
	v_mov_b32_e32 v100, v129
	v_mov_b32_e32 v99, v129
	v_mov_b32_e32 v98, v129
	v_mov_b32_e32 v69, v129
	v_mov_b32_e32 v68, v129
	v_mov_b32_e32 v67, v129
	v_mov_b32_e32 v66, v129
	v_mov_b32_e32 v49, v129
	v_mov_b32_e32 v48, v129
	v_mov_b32_e32 v47, v129
	v_mov_b32_e32 v46, v129
	v_mov_b32_e32 v17, v129
	v_mov_b32_e32 v16, v129
	v_mov_b32_e32 v15, v129
	v_mov_b32_e32 v14, v129
	v_mov_b32_e32 v45, v129
	v_mov_b32_e32 v44, v129
	v_mov_b32_e32 v43, v129
	v_mov_b32_e32 v42, v129
	v_mov_b32_e32 v13, v129
	v_mov_b32_e32 v12, v129
	v_mov_b32_e32 v11, v129
	v_mov_b32_e32 v10, v129
	v_mov_b32_e32 v41, v129
	v_mov_b32_e32 v40, v129
	v_mov_b32_e32 v39, v129
	v_mov_b32_e32 v38, v129
	v_mov_b32_e32 v9, v129
	v_mov_b32_e32 v8, v129
	v_mov_b32_e32 v7, v129
	v_mov_b32_e32 v6, v129
	v_mov_b32_e32 v37, v129
	v_mov_b32_e32 v36, v129
	v_mov_b32_e32 v35, v129
	v_mov_b32_e32 v34, v129
	v_mov_b32_e32 v5, v129
	v_mov_b32_e32 v4, v129
	v_mov_b32_e32 v3, v129
	v_mov_b32_e32 v2, v129
	s_branch .LBB0_1460
